# DSA online softmax: the row reference enters the QK MFMAs as C operand (persistent 16-register tuple), the 32 per-tile subtractions run only on tiles where the reference moves
# speedup vs baseline: 1.0176x; 1.0024x over previous
; template <int MODE>
; __device__ __forceinline__ void attn_unit(LAS char* lds, const AttnPtrs& A, int b, int qb) {
;     ...
;     const int tid = opaque_tid(), lane = tid & 63, r32 = lane & 31, hi = lane >> 5, wid = __builtin_amdgcn_readfirstlane(tid >> 6);
;     const int strm = (MODE == 2) ? (wid & 1) : 0;
;     const size_t rowbase = (size_t)b * SEQ; const int q0 = (MODE == 2) ? qb * 128 + (wid >> 1) * 32 : qb * 256 + wid * 32; const int cw = q0 >> 6, NT = (MODE == 2) ? 2 * qb + 2 : 4 * qb + 4;
;     const size_t qrow = rowbase + q0 + r32;
;     const bf16_t* ksrc[2]; const bf16_t* vsrc[2];
; #pragma unroll
;     for (int i = 0; i < 2; ++i) { const unsigned row = 4u * (2 * wid + i) + (lane >> 4), ch = (lane & 15) ^ (((row & 3) << 2) | ((row >> 2) & 3));
;         ksrc[i] = A.K + (rowbase + row) * A.ldk + ch * 8; vsrc[i] = A.V + (rowbase + row) * A.ldv + ch * 8; }
;     const bf16_t* k64src = nullptr;
;     if constexpr (MODE == 0) { const unsigned row = 8u * wid + (lane >> 3), ch = (lane & 7) ^ ((row >> 1) & 7); k64src = A.K64 + (rowbase + row) * 64 + ch * 8; }
;     const unsigned fK = ((r32 & 3) << 2) | ((r32 >> 2) & 3);
;     const unsigned g64 = (r32 >> 1) & 7;
;     const int q4 = (lane & 15) >> 2, p4 = lane & 3, blk = (lane >> 4) & 1;
;     unsigned vrow[2], vlow[2];
; #pragma unroll
;     for (int t = 0; t < 2; ++t) { vrow[t] = 4 * hi + 8 * t + q4; vlow[t] = (unsigned)((2 * blk + (p4 >> 1)) ^ ((hi + 2 * t) & 3)); }
;     ...
;     STAGE(0, 0); STAGE(1, 1);
;     bf16x8 qf[NQ];
; #pragma unroll
;     for (int s = 0; s < NQ; ++s) qf[s] = *(const bf16x8*)(A.Q + qrow * A.ldq + 64 * strm + 16 * s + 8 * hi);
;     if constexpr (MODE == 0) {
; #pragma unroll
;         for (int s = 0; s < 4; ++s) {
;             const u32x4 w = __builtin_bit_cast(u32x4, qf[8 + s]);
;             const f32x4 t0 = *(const f32x4*)(A.subg + (qrow * 56 + 8 * s + 4 * hi) * 2), t1 = *(const f32x4*)(A.subg + (qrow * 56 + 8 * s + 4 * hi) * 2 + 4);
;             u32x4 o;
;             { const float a = bf_lo(w.x), b = bf_hi(w.x); o.x = cvtpk(a * t0[0] - b * t0[1], b * t0[0] + a * t0[1]); }
;             { const float a = bf_lo(w.y), b = bf_hi(w.y); o.y = cvtpk(a * t0[2] - b * t0[3], b * t0[2] + a * t0[3]); }
;             { const float a = bf_lo(w.z), b = bf_hi(w.z); o.z = cvtpk(a * t1[0] - b * t1[1], b * t1[0] + a * t1[1]); }
.LBB0_1168:
	s_mul_hi_i32 s1, s0, 0xd1745d17
	s_lshr_b32 s12, s1, 31
	s_ashr_i32 s1, s1, 3
	s_add_i32 s49, s1, s12
	s_mul_hi_i32 s1, s0, 0x2e8ba2e9
	s_lshr_b32 s12, s1, 31
	s_ashr_i32 s1, s1, 3
	s_add_i32 s1, s1, s12
	s_mul_i32 s1, s1, 44
	s_add_i32 s49, s49, 15
	s_sub_i32 s14, s0, s1
	s_cmp_gt_i32 s14, 23
	s_mov_b64 s[0:1], -1
	s_cbranch_scc0 .LBB0_1186
	s_add_i32 s0, s14, 0xffe8
	s_and_b32 s12, s0, 0xff
	s_mul_i32 s1, s12, 0xcd
	s_bfe_u32 s13, s1, 0x6000a
	s_mul_i32 s1, s13, 5
	s_sub_i32 s0, s0, s1
	s_and_b32 s0, s0, 0xff
	s_lshl_b32 s15, s0, 7
	s_lshl_b32 s16, s0, 8
	s_add_u32 s0, s21, s16
	s_addc_u32 s1, s22, 0
	s_add_u32 s50, s23, s16
	s_addc_u32 s51, s24, 0
	s_add_u32 s52, s25, s16
	s_getreg_b32 s17, hwreg(HW_REG_HW_ID, 0, 6)
	s_addc_u32 s53, s26, 0
	s_lshl_b32 s17, s17, 2
	s_and_b32 s17, s17, 0xfc
	s_add_i32 s17, s17, 0x20040
	v_mov_b32_e32 v0, s17
	ds_read_b32 v0, v0
	s_lshl_b32 s68, s13, 12
	v_mov_b64_e32 v[6:7], s[50:51]
	v_mov_b32_e32 v3, v1
	s_mul_i32 s13, s13, 0x9ffb00
	s_waitcnt lgkmcnt(0)
	v_readfirstlane_b32 s18, v0
	v_mov_b32_e32 v0, v1
	s_mov_b32 s16, 2
	v_mbcnt_lo_u32_b32 v0, -1, v0
	v_mbcnt_hi_u32_b32 v8, -1, v0
	v_lshl_or_b32 v0, s18, 6, v8
	v_bfe_u32 v9, v8, 4, 2
	v_readfirstlane_b32 s18, v0
	s_ashr_i32 s19, s18, 6
	s_lshl_b32 s18, s49, 8
	s_lshl_b32 s33, s19, 5
	s_add_i32 s54, s33, s18
	s_lshl_b32 s18, s19, 3
	v_or_b32_e32 v0, s18, v9
	s_lshl_b32 s56, s19, 1
	v_and_b32_e32 v13, 15, v8
	v_lshlrev_b32_e32 v20, 2, v9
	s_and_b32 s56, s56, 2
	v_lshl_add_u64 v[4:5], s[68:69], 0, v[0:1]
	v_bitop3_b32 v2, s56, v13, v20 bitop3:0x36
	v_mad_u64_u32 v[10:11], s[50:51], v4, s84, v[6:7]
	v_mad_u32_u24 v11, v5, s84, v11
	v_lshlrev_b32_e32 v2, 4, v2
	v_lshl_add_u64 v[16:17], v[10:11], 0, v[2:3]
	v_mov_b64_e32 v[10:11], s[52:53]
	v_mad_u64_u32 v[14:15], s[50:51], v4, s84, v[10:11]
	s_or_b32 s18, s18, 4
	v_mad_u32_u24 v15, v5, s84, v15
	v_or_b32_e32 v4, s18, v9
	v_mov_b32_e32 v5, v1
	v_lshl_add_u64 v[18:19], v[14:15], 0, v[2:3]
	s_bfe_u32 s18, s18, 0x20002
	v_lshl_add_u64 v[14:15], s[68:69], 0, v[4:5]
	s_lshl_b32 s33, s49, 2
	s_ashr_i32 s55, s54, 31
	v_bitop3_b32 v9, s18, v13, v20 bitop3:0x36
	v_mad_u64_u32 v[6:7], s[50:51], v14, s84, v[6:7]
	v_mad_u64_u32 v[10:11], s[50:51], v14, s84, v[10:11]
	s_ashr_i32 s18, s54, 6
	s_add_u32 s50, s68, s54
	s_addc_u32 s51, 0, s55
	s_lshl_b32 s19, s19, 11
	s_add_i32 s19, s19, 0
	v_mad_u32_u24 v7, v15, s84, v7
	v_lshlrev_b32_e32 v4, 4, v9
	s_mov_b32 m0, s19
	v_lshl_add_u64 v[6:7], v[6:7], 0, v[4:5]
	global_load_lds_dwordx4 v[16:17], off
	s_add_i32 m0, s19, 0x400
	v_mad_u32_u24 v11, v15, s84, v11
	global_load_lds_dwordx4 v[6:7], off
	s_add_i32 m0, s19, 0x4000
	v_lshl_add_u64 v[20:21], v[10:11], 0, v[4:5]
	global_load_lds_dwordx4 v[18:19], off
	s_add_i32 m0, s19, 0x4400
	v_lshl_add_u64 v[16:17], v[16:17], 0, s[60:61]
	global_load_lds_dwordx4 v[20:21], off
	s_add_i32 m0, s19, 0xa000
	v_lshl_add_u64 v[6:7], v[6:7], 0, s[60:61]
	global_load_lds_dwordx4 v[16:17], off
	s_add_i32 m0, s19, 0xa400
	v_and_b32_e32 v12, 31, v8
	global_load_lds_dwordx4 v[6:7], off
	v_lshl_add_u64 v[6:7], v[18:19], 0, s[60:61]
	s_add_i32 m0, s19, 0xe000
	v_or_b32_e32 v130, s50, v12
	global_load_lds_dwordx4 v[6:7], off
	v_lshl_add_u64 v[6:7], v[20:21], 0, s[60:61]
	s_add_i32 m0, s19, 0xe400
	v_bfe_u32 v9, v8, 5, 1
	global_load_lds_dwordx4 v[6:7], off
	v_mov_b64_e32 v[6:7], s[0:1]
	v_mad_u64_u32 v[6:7], s[0:1], v130, s84, v[6:7]
	v_mov_b32_e32 v16, 0xa00
	v_mad_i32_i24 v7, s51, v16, v7
	v_lshlrev_b32_e32 v16, 4, v9
	v_mov_b32_e32 v17, v1
	v_lshl_add_u64 v[6:7], v[6:7], 0, v[16:17]
	global_load_dwordx4 v[98:101], v[6:7], off
	global_load_dwordx4 v[102:105], v[6:7], off offset:32
	global_load_dwordx4 v[106:109], v[6:7], off offset:64
	global_load_dwordx4 v[110:113], v[6:7], off offset:96
	global_load_dwordx4 v[114:117], v[6:7], off offset:128
	global_load_dwordx4 v[118:121], v[6:7], off offset:160
	global_load_dwordx4 v[122:125], v[6:7], off offset:192
	global_load_dwordx4 v[126:129], v[6:7], off offset:224
	v_mov_b32_e32 v131, s51
	v_lshlrev_b64 v[6:7], 9, v[130:131]
	v_lshlrev_b32_e32 v22, 2, v8
	v_lshl_add_u64 v[16:17], s[6:7], 0, v[6:7]
	v_bfe_u32 v23, v8, 2, 2
	v_and_b32_e32 v22, 12, v22
	v_lshlrev_b32_e32 v141, 8, v12
	v_lshlrev_b32_e32 v12, 3, v8
	v_or_b32_e32 v24, v22, v23
	v_lshrrev_b32_e32 v10, 3, v8
	s_waitcnt vmcnt(0)
	global_load_dwordx2 v[132:133], v[16:17], off
	v_mov_b32_e32 v16, 0x4000
	v_and_or_b32 v142, v12, 8, v16
	v_bitop3_b32 v12, v22, v9, v23 bitop3:0x36
	v_lshlrev_b32_e32 v143, 4, v12
	v_bitop3_b32 v12, v9, v24, 2 bitop3:0x36
	v_lshlrev_b32_e32 v144, 4, v12
	v_bitop3_b32 v12, v9, v24, 4 bitop3:0x36
	v_lshlrev_b32_e32 v145, 4, v12
	v_bitop3_b32 v12, v9, v24, 6 bitop3:0x36
	v_lshlrev_b32_e32 v146, 4, v12
	v_bitop3_b32 v12, v9, v24, 8 bitop3:0x36
	v_lshlrev_b32_e32 v147, 4, v12
	v_bitop3_b32 v12, v9, v24, 10 bitop3:0x36
	v_and_b32_e32 v11, 2, v10
	v_bfe_u32 v13, v8, 1, 1
	v_lshlrev_b32_e32 v148, 4, v12
	v_bitop3_b32 v12, v9, v24, 12 bitop3:0x36
	v_lshlrev_b32_e32 v140, 2, v9
	v_or_b32_e32 v10, v13, v11
	v_lshlrev_b32_e32 v149, 4, v12
	v_bitop3_b32 v12, v9, v24, 14 bitop3:0x36
	v_or_b32_e32 v14, v140, v23
	v_bitop3_b32 v15, v13, v9, v11 bitop3:0x36
	v_bitop3_b32 v13, v9, v10, 2 bitop3:0x36
	v_lshlrev_b32_e32 v150, 4, v12
	v_and_b32_e32 v12, 12, v8
	v_lshlrev_b32_e32 v151, 8, v14
	v_or_b32_e32 v14, v15, v12
	v_or_b32_e32 v12, v13, v12
	v_or_b32_e32 v11, 2, v9
	v_lshlrev_b32_e32 v154, 4, v12
	v_bitop3_b32 v12, v8, 4, 12 bitop3:0x6c
	s_mov_b64 s[0:1], 0x2d990000
	s_add_i32 s33, s33, 4
	v_bitop3_b32 v13, v10, v12, v9 bitop3:0xde
	v_bitop3_b32 v12, v11, v12, v10 bitop3:0xde
	v_lshl_add_u64 v[134:135], v[6:7], 0, s[0:1]
	s_lshl_b32 s0, s12, 8
	v_lshlrev_b32_e32 v178, 4, v12
	v_bitop3_b32 v12, v8, 8, 12 bitop3:0x6c
	v_bitop3_b32 v8, v8, 12, v8 bitop3:0xc
	s_add_u32 s0, s0, s13
	v_lshlrev_b32_e32 v177, 4, v13
	v_bitop3_b32 v13, v10, v12, v9 bitop3:0xde
	v_bitop3_b32 v9, v10, v8, v9 bitop3:0xde
	v_bitop3_b32 v8, v11, v8, v10 bitop3:0xde
	s_addc_u32 s1, 0, 0
	v_lshlrev_b32_e32 v182, 4, v8
	v_or_b32_e32 v8, 4, v0
	v_mov_b64_e32 v[6:7], s[0:1]
	v_lshlrev_b32_e32 v181, 4, v9
	v_mad_u64_u32 v[8:9], s[0:1], v8, s84, v[6:7]
	v_lshlrev_b32_e32 v152, 4, v14
	v_bitop3_b32 v12, v11, v12, v10 bitop3:0xde
	v_lshl_add_u64 v[136:137], v[8:9], 0, v[4:5]
	v_mad_u64_u32 v[4:5], s[0:1], v0, s84, v[6:7]
	v_mov_b32_e32 v14, v1
	v_mov_b32_e32 v15, v1
	s_waitcnt vmcnt(0)
	s_waitcnt vmcnt(0) lgkmcnt(0)
	s_barrier
; template <int MODE>
; __device__ __forceinline__ void attn_unit(LAS char* lds, const AttnPtrs& A, int b, int qb) {
;     ...
;     f32x16 o1[4];
; #pragma unroll
;     for (int c = 0; c < 4; ++c) o1[c] = f32x16{};
;     float m1 = -1e30f, l1 = 0.f;
;     unsigned long long mw_next = 0ull;
;     if constexpr (MODE == 1) { mw_next = A.MASK[qrow * 64]; asm volatile("" : "+v"(mw_next)); }
;     bf16x8 pk[4]; float a1 = 1.f;
;     ...
;     int st_cur = 0, st_nn = 2;
;     for (int t = 0; t < NT; ++t) {
;         unsigned mlo = 0, mhi = 0;
;         if constexpr (MODE == 1) { if (t <= cw) {
;             const unsigned long long w = mw_next; mlo = (unsigned)w >> (4 * hi); mhi = (unsigned)(w >> 32) >> (4 * hi);
;             asm volatile("" : "+v"(mlo), "+v"(mhi));
;             if (t < cw) { const unsigned long long* mp_ = A.MASK + qrow * 64 + t + 1; asm volatile("global_load_dwordx2 %0, %1, off" : "+v"(mw_next) : "v"(mp_) : "memory"); } } }
;         const bool more2 = (t + 2 < NT);
;         if (more2) STAGE(t + 2, st_nn);
;         if (t <= cw) {
	v_lshlrev_b32_e32 v179, 4, v13
	v_lshlrev_b32_e32 v180, 4, v12
	v_lshl_add_u64 v[138:139], v[4:5], 0, v[2:3]
	v_mov_b32_e32 v0, v1
	v_mov_b32_e32 v2, v1
	v_mov_b32_e32 v4, v1
	v_mov_b32_e32 v5, v1
	v_mov_b32_e32 v6, v1
	v_mov_b32_e32 v7, v1
	v_mov_b32_e32 v8, v1
	v_mov_b32_e32 v9, v1
	v_mov_b32_e32 v10, v1
	v_mov_b32_e32 v11, v1
	v_mov_b32_e32 v12, v1
	v_mov_b32_e32 v13, v1
	v_mov_b64_e32 v[64:65], v[14:15]
	v_mov_b64_e32 v[48:49], v[14:15]
	v_mov_b64_e32 v[32:33], v[14:15]
	v_mov_b64_e32 v[62:63], v[12:13]
	v_mov_b64_e32 v[60:61], v[10:11]
	v_mov_b64_e32 v[58:59], v[8:9]
	v_mov_b64_e32 v[56:57], v[6:7]
	v_mov_b64_e32 v[54:55], v[4:5]
	v_mov_b64_e32 v[52:53], v[2:3]
	v_mov_b64_e32 v[50:51], v[0:1]
	v_mov_b64_e32 v[46:47], v[12:13]
	v_mov_b64_e32 v[44:45], v[10:11]
	v_mov_b64_e32 v[42:43], v[8:9]
	v_mov_b64_e32 v[40:41], v[6:7]
	v_mov_b64_e32 v[38:39], v[4:5]
	v_mov_b64_e32 v[36:37], v[2:3]
	v_mov_b64_e32 v[34:35], v[0:1]
	v_mov_b64_e32 v[30:31], v[12:13]
	v_mov_b64_e32 v[28:29], v[10:11]
	v_mov_b64_e32 v[26:27], v[8:9]
	v_mov_b64_e32 v[24:25], v[6:7]
	v_mov_b64_e32 v[22:23], v[4:5]
	v_mov_b64_e32 v[20:21], v[2:3]
	v_mov_b64_e32 v[18:19], v[0:1]
	v_mov_b64_e32 v[16:17], v[14:15]
	s_mov_b32 s17, 0
	v_or_b32_e32 v153, 0x800, v151
	v_or_b32_e32 v155, 0x1000, v151
	v_or_b32_e32 v156, 0x1800, v151
	v_or_b32_e32 v157, 0x2000, v151
	v_or_b32_e32 v158, 0x2800, v151
	v_or_b32_e32 v159, 0x3000, v151
	v_or_b32_e32 v176, 0x3800, v151
	v_mov_b32_e32 v184, 0xf149f2ca
	v_mov_b32_e32 v252, 0
	v_mov_b64_e32 v[236:237], 0
	v_mov_b64_e32 v[238:239], 0
	v_mov_b64_e32 v[240:241], 0
	v_mov_b64_e32 v[242:243], 0
	v_mov_b64_e32 v[244:245], 0
	v_mov_b64_e32 v[246:247], 0
	v_mov_b64_e32 v[248:249], 0
	v_mov_b64_e32 v[250:251], 0
	v_mov_b32_e32 v183, 0
	v_mov_b64_e32 v[14:15], v[12:13]
	v_mov_b64_e32 v[12:13], v[10:11]
	v_mov_b64_e32 v[10:11], v[8:9]
	v_mov_b64_e32 v[8:9], v[6:7]
	v_mov_b64_e32 v[6:7], v[4:5]
	v_mov_b64_e32 v[4:5], v[2:3]
	v_mov_b64_e32 v[2:3], v[0:1]
	s_mov_b32 s50, 0
	s_cmp_le_i32 s50, s18
	s_cselect_b64 s[12:13], -1, 0
	s_cmp_gt_i32 s50, s18
	s_cbranch_scc1 .LBB0_1171
	s_branch .LBB0_1172

; __device__ __forceinline__ float max_x32(float v) { const unsigned u = __float_as_uint(v); auto r = __builtin_amdgcn_permlane32_swap(u, u, false, false); return fmaxf(__uint_as_float(r[0]), __uint_as_float(r[1])); }
; template <bool MASKED>
; __device__ __forceinline__ void softmax_tile(f32x16& s0, f32x16& s1, float& m, float& l, float& alpha, unsigned mlo, unsigned mhi, bf16x8 (&pk)[4]) {
;     ...
;         for (int r = 0; r < 16; ++r) { const int bit = (r & 3) + 8 * (r >> 2); if (!((mlo >> bit) & 1u)) s0[r] = NEG; if (!((mhi >> bit) & 1u)) s1[r] = NEG; }
;     }
;     float mx = fmaxf(s0[0], s1[0]);
; #pragma unroll
;     for (int r = 1; r < 16; ++r) mx = fmaxf(mx, fmaxf(s0[r], s1[r]));
;     mx = max_x32(mx);
;     const float mn = fmaxf(m, mx);
;     alpha = __builtin_amdgcn_exp2f(m - mn); m = mn;
.LBB0_1176:
	s_andn2_b64 vcc, exec, s[12:13]
	s_cbranch_vccnz .LBB0_1180
	s_mul_i32 s12, s17, 0xa000
	s_add_i32 s12, s12, 0
	v_add_u32_e32 v194, s12, v141
	v_add_u32_e32 v70, v194, v143
	v_add_u32_e32 v74, v194, v144
	ds_read_b128 v[66:69], v70
	ds_read_b128 v[70:73], v70 offset:8192
	ds_read_b128 v[160:163], v74
	ds_read_b128 v[164:167], v74 offset:8192
	v_add_u32_e32 v74, v194, v145
	ds_read_b128 v[168:171], v74
	ds_read_b128 v[172:175], v74 offset:8192
	v_add_u32_e32 v74, v194, v146
	ds_read_b128 v[186:189], v74 offset:8192
	ds_read_b128 v[190:193], v74
	s_waitcnt lgkmcnt(0)
	v_mfma_f32_32x32x16_bf16 v[82:97], v[66:69], v[98:101], v[236:251]
	v_mfma_f32_32x32x16_bf16 v[66:81], v[70:73], v[98:101], v[236:251]
	v_mfma_f32_32x32x16_bf16 v[82:97], v[160:163], v[102:105], v[82:97]
	v_mfma_f32_32x32x16_bf16 v[66:81], v[164:167], v[102:105], v[66:81]
	v_mfma_f32_32x32x16_bf16 v[82:97], v[168:171], v[106:109], v[82:97]
	v_mfma_f32_32x32x16_bf16 v[66:81], v[172:175], v[106:109], v[66:81]
	v_mfma_f32_32x32x16_bf16 v[82:97], v[190:193], v[110:113], v[82:97]
	v_mfma_f32_32x32x16_bf16 v[66:81], v[186:189], v[110:113], v[66:81]
	v_add_u32_e32 v164, v194, v147
	v_add_u32_e32 v172, v194, v148
	v_add_u32_e32 v190, v194, v149
	v_add_u32_e32 v198, v194, v150
	ds_read_b128 v[160:163], v164
	ds_read_b128 v[164:167], v164 offset:8192
	ds_read_b128 v[168:171], v172
	ds_read_b128 v[172:175], v172 offset:8192
	ds_read_b128 v[186:189], v190
	ds_read_b128 v[190:193], v190 offset:8192
	ds_read_b128 v[194:197], v198 offset:8192
	ds_read_b128 v[206:209], v198
	s_waitcnt lgkmcnt(0)
	v_mfma_f32_32x32x16_bf16 v[82:97], v[160:163], v[114:117], v[82:97]
	v_mfma_f32_32x32x16_bf16 v[66:81], v[164:167], v[114:117], v[66:81]
	v_mfma_f32_32x32x16_bf16 v[82:97], v[168:171], v[118:121], v[82:97]
	v_mfma_f32_32x32x16_bf16 v[66:81], v[172:175], v[118:121], v[66:81]
	v_mfma_f32_32x32x16_bf16 v[82:97], v[186:189], v[122:125], v[82:97]
	v_mfma_f32_32x32x16_bf16 v[66:81], v[190:193], v[122:125], v[66:81]
	v_mfma_f32_32x32x16_bf16 v[82:97], v[206:209], v[126:129], v[82:97]
	v_mfma_f32_32x32x16_bf16 v[66:81], v[194:197], v[126:129], v[66:81]
	v_bfe_i32 v160, v185, 0, 1
	v_bfe_i32 v161, v185, 1, 1
	v_bfe_i32 v162, v185, 2, 1
	v_bfe_i32 v163, v185, 3, 1
	v_bfe_i32 v164, v185, 8, 1
	v_bfe_i32 v165, v185, 9, 1
	v_bfe_i32 v166, v185, 10, 1
	v_bfe_i32 v167, v185, 11, 1
	v_bfe_i32 v168, v185, 16, 1
	v_bfe_i32 v169, v185, 17, 1
	v_bfe_i32 v170, v185, 18, 1
	v_bfe_i32 v171, v185, 19, 1
	v_bfe_i32 v172, v185, 24, 1
	v_bfe_i32 v173, v185, 25, 1
	v_bfe_i32 v174, v185, 26, 1
	v_bfe_i32 v175, v185, 27, 1
	v_bfe_i32 v186, v0, 0, 1
	v_bfe_i32 v187, v0, 1, 1
	v_bfe_i32 v188, v0, 2, 1
	v_bfe_i32 v189, v0, 3, 1
	v_bfe_i32 v190, v0, 8, 1
	v_bfe_i32 v191, v0, 9, 1
	v_bfe_i32 v192, v0, 10, 1
	v_bfe_i32 v193, v0, 11, 1
	v_bfe_i32 v194, v0, 16, 1
	v_bfe_i32 v195, v0, 17, 1
	v_bfe_i32 v196, v0, 18, 1
	v_bfe_i32 v197, v0, 19, 1
	v_bfe_i32 v198, v0, 24, 1
	v_bfe_i32 v199, v0, 25, 1
	v_bfe_i32 v206, v0, 26, 1
	v_bfe_i32 v207, v0, 27, 1
	v_bfi_b32 v82, v160, v82, v215
	v_bfi_b32 v83, v161, v83, v215
	v_bfi_b32 v84, v162, v84, v215
	v_bfi_b32 v85, v163, v85, v215
	v_bfi_b32 v86, v164, v86, v215
	v_bfi_b32 v87, v165, v87, v215
	v_bfi_b32 v88, v166, v88, v215
	v_bfi_b32 v89, v167, v89, v215
	v_bfi_b32 v90, v168, v90, v215
	v_bfi_b32 v91, v169, v91, v215
	v_bfi_b32 v92, v170, v92, v215
	v_bfi_b32 v93, v171, v93, v215
	v_bfi_b32 v94, v172, v94, v215
	v_bfi_b32 v95, v173, v95, v215
	v_bfi_b32 v96, v174, v96, v215
	v_bfi_b32 v97, v175, v97, v215
	v_bfi_b32 v66, v186, v66, v215
	v_bfi_b32 v67, v187, v67, v215
	v_bfi_b32 v68, v188, v68, v215
	v_bfi_b32 v69, v189, v69, v215
	v_bfi_b32 v70, v190, v70, v215
	v_bfi_b32 v71, v191, v71, v215
	v_bfi_b32 v72, v192, v72, v215
	v_bfi_b32 v73, v193, v73, v215
	v_bfi_b32 v74, v194, v74, v215
	v_bfi_b32 v75, v195, v75, v215
	v_bfi_b32 v76, v196, v76, v215
	v_bfi_b32 v77, v197, v77, v215
	v_bfi_b32 v78, v198, v78, v215
	v_bfi_b32 v79, v199, v79, v215
	v_bfi_b32 v80, v206, v80, v215
	v_bfi_b32 v81, v207, v81, v215
	v_max3_f32 v160, v82, v83, v84
	v_max3_f32 v161, v85, v86, v87
	v_max3_f32 v162, v88, v89, v90
	v_max3_f32 v163, v91, v92, v93
	v_max3_f32 v164, v94, v95, v96
	v_max3_f32 v165, v97, v66, v67
	v_max3_f32 v166, v68, v69, v70
	v_max3_f32 v167, v71, v72, v73
	v_max3_f32 v168, v74, v75, v76
	v_max3_f32 v169, v77, v78, v79
	v_max3_f32 v160, v160, v161, v162
	v_max3_f32 v163, v163, v164, v165
	v_max3_f32 v166, v166, v167, v168
	v_max3_f32 v169, v169, v80, v81
	v_max3_f32 v160, v160, v163, v166
	v_max_f32_e32 v160, v160, v169
	v_mov_b32_e32 v161, v160
	s_nop 1
	v_permlane32_swap_b32_e32 v160, v161
	v_max_f32_e32 v162, v160, v161
	v_add_f32_e32 v162, v162, v252
	v_max3_f32 v162, v184, v162, s97
	v_sub_f32_e32 v163, v162, v184
	v_cmp_lt_f32_e32 vcc, 8.0, v163
	s_nop 1
	v_cndmask_b32_e32 v162, v184, v162, vcc
	v_sub_f32_e32 v0, v184, v162
	v_sub_f32_e32 v163, v162, v252
	v_cmp_lt_f32_e32 vcc, s97, v162
	s_nop 1
	v_cndmask_b32_e32 v163, 0, v163, vcc
	v_cndmask_b32_e32 v253, v252, v162, vcc
	v_cmp_neq_f32_e32 vcc, 0, v163
	s_cbranch_vccz .Lm1_cfast
	v_sub_f32_e32 v82, v82, v163
	v_sub_f32_e32 v83, v83, v163
	v_sub_f32_e32 v84, v84, v163
	v_sub_f32_e32 v85, v85, v163
	v_sub_f32_e32 v86, v86, v163
	v_sub_f32_e32 v87, v87, v163
	v_sub_f32_e32 v88, v88, v163
	v_sub_f32_e32 v89, v89, v163
	v_sub_f32_e32 v90, v90, v163
	v_sub_f32_e32 v91, v91, v163
	v_sub_f32_e32 v92, v92, v163
	v_sub_f32_e32 v93, v93, v163
	v_sub_f32_e32 v94, v94, v163
	v_sub_f32_e32 v95, v95, v163
	v_sub_f32_e32 v96, v96, v163
	v_sub_f32_e32 v97, v97, v163
	v_sub_f32_e32 v66, v66, v163
	v_sub_f32_e32 v67, v67, v163
	v_sub_f32_e32 v68, v68, v163
	v_sub_f32_e32 v69, v69, v163
	v_sub_f32_e32 v70, v70, v163
	v_sub_f32_e32 v71, v71, v163
	v_sub_f32_e32 v72, v72, v163
	v_sub_f32_e32 v73, v73, v163
	v_sub_f32_e32 v74, v74, v163
	v_sub_f32_e32 v75, v75, v163
	v_sub_f32_e32 v76, v76, v163
	v_sub_f32_e32 v77, v77, v163
	v_sub_f32_e32 v78, v78, v163
	v_sub_f32_e32 v79, v79, v163
	v_sub_f32_e32 v80, v80, v163
	v_sub_f32_e32 v81, v81, v163
	v_mov_b32_e32 v252, v253
	v_sub_f32_e32 v236, 0, v253
	v_sub_f32_e32 v237, 0, v253
	v_sub_f32_e32 v238, 0, v253
	v_sub_f32_e32 v239, 0, v253
	v_sub_f32_e32 v240, 0, v253
	v_sub_f32_e32 v241, 0, v253
	v_sub_f32_e32 v242, 0, v253
	v_sub_f32_e32 v243, 0, v253
	v_sub_f32_e32 v244, 0, v253
	v_sub_f32_e32 v245, 0, v253
	v_sub_f32_e32 v246, 0, v253
	v_sub_f32_e32 v247, 0, v253
	v_sub_f32_e32 v248, 0, v253
	v_sub_f32_e32 v249, 0, v253
	v_sub_f32_e32 v250, 0, v253
	v_sub_f32_e32 v251, 0, v253
; __device__ __forceinline__ unsigned cvtpk(float lo, float hi) { unsigned r; asm("v_cvt_pk_bf16_f32 %0, %1, %2" : "=v"(r) : "v"(lo), "v"(hi)); return r; }
; template <bool MASKED>
; __device__ __forceinline__ void softmax_tile(f32x16& s0, f32x16& s1, float& m, float& l, float& alpha, unsigned mlo, unsigned mhi, bf16x8 (&pk)[4]) {
;     ...
;     alpha = __builtin_amdgcn_exp2f(m - mn); m = mn;
;     float sum = 0.f;
; #pragma unroll
;     for (int r = 0; r < 16; ++r) {
;         float p0 = __builtin_amdgcn_exp2f(s0[r] - mn), p1 = __builtin_amdgcn_exp2f(s1[r] - mn);
;         if (MASKED) { if (s0[r] <= -1e29f) p0 = 0.f; if (s1[r] <= -1e29f) p1 = 0.f; }
;         s0[r] = p0; s1[r] = p1; sum += p0 + p1;
;     }
;     l = l * alpha + sum;
; #pragma unroll
;     for (int k2 = 0; k2 < 2; ++k2) {
;         u32x4 a, b;
;         a.x = cvtpk(s0[8 * k2 + 0], s0[8 * k2 + 1]); a.y = cvtpk(s0[8 * k2 + 2], s0[8 * k2 + 3]); a.z = cvtpk(s0[8 * k2 + 4], s0[8 * k2 + 5]); a.w = cvtpk(s0[8 * k2 + 6], s0[8 * k2 + 7]);
;         b.x = cvtpk(s1[8 * k2 + 0], s1[8 * k2 + 1]); b.y = cvtpk(s1[8 * k2 + 2], s1[8 * k2 + 3]); b.z = cvtpk(s1[8 * k2 + 4], s1[8 * k2 + 5]); b.w = cvtpk(s1[8 * k2 + 6], s1[8 * k2 + 7]);
;         pk[k2] = __builtin_bit_cast(bf16x8, a); pk[2 + k2] = __builtin_bit_cast(bf16x8, b);
;     }
.Lm1_cfast:
	v_exp_f32_e32 v0, v0
	v_exp_f32_e32 v82, v82
	v_exp_f32_e32 v83, v83
	v_exp_f32_e32 v84, v84
	v_exp_f32_e32 v85, v85
	v_exp_f32_e32 v86, v86
	v_exp_f32_e32 v87, v87
	v_exp_f32_e32 v88, v88
	v_exp_f32_e32 v89, v89
	v_exp_f32_e32 v90, v90
	v_exp_f32_e32 v91, v91
	v_exp_f32_e32 v92, v92
	v_exp_f32_e32 v93, v93
	v_exp_f32_e32 v94, v94
	v_exp_f32_e32 v95, v95
	v_exp_f32_e32 v96, v96
	v_exp_f32_e32 v97, v97
	v_exp_f32_e32 v66, v66
	v_exp_f32_e32 v67, v67
	v_exp_f32_e32 v68, v68
	v_exp_f32_e32 v69, v69
	v_exp_f32_e32 v70, v70
	v_exp_f32_e32 v71, v71
	v_exp_f32_e32 v72, v72
	v_exp_f32_e32 v73, v73
	v_exp_f32_e32 v74, v74
	v_exp_f32_e32 v75, v75
	v_exp_f32_e32 v76, v76
	v_exp_f32_e32 v77, v77
	v_exp_f32_e32 v78, v78
	v_exp_f32_e32 v79, v79
	v_exp_f32_e32 v80, v80
	v_exp_f32_e32 v81, v81
	v_pk_add_f32 v[164:165], v[82:83], v[84:85]
	v_pk_add_f32 v[166:167], v[86:87], v[88:89]
	v_pk_add_f32 v[168:169], v[90:91], v[92:93]
	v_pk_add_f32 v[170:171], v[94:95], v[96:97]
	v_pk_add_f32 v[172:173], v[66:67], v[68:69]
	v_pk_add_f32 v[174:175], v[70:71], v[72:73]
	v_pk_add_f32 v[186:187], v[74:75], v[76:77]
	v_pk_add_f32 v[188:189], v[78:79], v[80:81]
	v_pk_add_f32 v[164:165], v[164:165], v[166:167]
	v_pk_add_f32 v[168:169], v[168:169], v[170:171]
	v_pk_add_f32 v[172:173], v[172:173], v[174:175]
	v_pk_add_f32 v[186:187], v[186:187], v[188:189]
	v_pk_add_f32 v[164:165], v[164:165], v[168:169]
	v_pk_add_f32 v[172:173], v[172:173], v[186:187]
	v_pk_add_f32 v[164:165], v[164:165], v[172:173]
	v_add_f32_e32 v164, v164, v165
	v_cvt_pk_bf16_f32 v66, v66, v67
	v_cvt_pk_bf16_f32 v67, v68, v69
	v_cvt_pk_bf16_f32 v68, v70, v71
	v_cvt_pk_bf16_f32 v69, v72, v73
	v_cvt_pk_bf16_f32 v70, v74, v75
	v_cvt_pk_bf16_f32 v71, v76, v77
	v_cvt_pk_bf16_f32 v72, v78, v79
	v_cvt_pk_bf16_f32 v73, v80, v81
	v_cvt_pk_bf16_f32 v74, v82, v83
	v_cvt_pk_bf16_f32 v75, v84, v85
	v_cvt_pk_bf16_f32 v76, v86, v87
	v_cvt_pk_bf16_f32 v77, v88, v89
	v_cvt_pk_bf16_f32 v78, v90, v91
	v_cvt_pk_bf16_f32 v79, v92, v93
	v_cvt_pk_bf16_f32 v80, v94, v95
	v_cvt_pk_bf16_f32 v81, v96, v97
	v_fmac_f32_e32 v164, v183, v0
	v_mov_b32_e32 v83, v164
	v_mov_b32_e32 v82, v162
	v_cmp_neq_f32_e32 vcc, 1.0, v0
	s_cbranch_vccz .LBB0_1179
	v_pk_mul_f32 v[64:65], v[64:65], v[0:1] op_sel_hi:[1,0]
	v_pk_mul_f32 v[62:63], v[62:63], v[0:1] op_sel_hi:[1,0]
	v_pk_mul_f32 v[60:61], v[60:61], v[0:1] op_sel_hi:[1,0]
	v_pk_mul_f32 v[58:59], v[58:59], v[0:1] op_sel_hi:[1,0]
	v_pk_mul_f32 v[56:57], v[56:57], v[0:1] op_sel_hi:[1,0]
	v_pk_mul_f32 v[54:55], v[54:55], v[0:1] op_sel_hi:[1,0]
	v_pk_mul_f32 v[52:53], v[52:53], v[0:1] op_sel_hi:[1,0]
	v_pk_mul_f32 v[50:51], v[50:51], v[0:1] op_sel_hi:[1,0]
	v_pk_mul_f32 v[48:49], v[48:49], v[0:1] op_sel_hi:[1,0]
	v_pk_mul_f32 v[46:47], v[46:47], v[0:1] op_sel_hi:[1,0]
	v_pk_mul_f32 v[44:45], v[44:45], v[0:1] op_sel_hi:[1,0]
	v_pk_mul_f32 v[42:43], v[42:43], v[0:1] op_sel_hi:[1,0]
	v_pk_mul_f32 v[40:41], v[40:41], v[0:1] op_sel_hi:[1,0]
	v_pk_mul_f32 v[38:39], v[38:39], v[0:1] op_sel_hi:[1,0]
	v_pk_mul_f32 v[36:37], v[36:37], v[0:1] op_sel_hi:[1,0]
	v_pk_mul_f32 v[34:35], v[34:35], v[0:1] op_sel_hi:[1,0]
	v_pk_mul_f32 v[32:33], v[32:33], v[0:1] op_sel_hi:[1,0]
	v_pk_mul_f32 v[30:31], v[30:31], v[0:1] op_sel_hi:[1,0]
	v_pk_mul_f32 v[28:29], v[28:29], v[0:1] op_sel_hi:[1,0]
	v_pk_mul_f32 v[26:27], v[26:27], v[0:1] op_sel_hi:[1,0]
	v_pk_mul_f32 v[24:25], v[24:25], v[0:1] op_sel_hi:[1,0]
	v_pk_mul_f32 v[22:23], v[22:23], v[0:1] op_sel_hi:[1,0]
	v_pk_mul_f32 v[20:21], v[20:21], v[0:1] op_sel_hi:[1,0]
	v_pk_mul_f32 v[18:19], v[18:19], v[0:1] op_sel_hi:[1,0]
	v_pk_mul_f32 v[16:17], v[16:17], v[0:1] op_sel_hi:[1,0]
	v_pk_mul_f32 v[14:15], v[14:15], v[0:1] op_sel_hi:[1,0]
	v_pk_mul_f32 v[12:13], v[12:13], v[0:1] op_sel_hi:[1,0]
	v_pk_mul_f32 v[10:11], v[10:11], v[0:1] op_sel_hi:[1,0]
	v_pk_mul_f32 v[8:9], v[8:9], v[0:1] op_sel_hi:[1,0]
	v_pk_mul_f32 v[6:7], v[6:7], v[0:1] op_sel_hi:[1,0]
	v_pk_mul_f32 v[4:5], v[4:5], v[0:1] op_sel_hi:[1,0]
	v_pk_mul_f32 v[2:3], v[2:3], v[0:1] op_sel_hi:[1,0]
